# phase 2: static item assignment (blocks 0..127 one compression item, blocks 128..511 mLSTM pre-pass items bid+384r) instead of an atomic queue pop per item
# speedup vs baseline: 1.0017x; 1.0017x over previous
.LBB0_339:
	s_or_b64 exec, exec, s[4:5]
	v_cmp_eq_u32_e64 s[40:41], 0, v200
	s_mov_b32 s32, 0
	s_branch .LBB0_342

.LBB0_342:
	v_readlane_b32 s0, v251, 5
	s_lshr_b32 s0, s0, 2
	s_cmpk_lt_u32 s0, 0x80
	s_cbranch_scc1 .Lp2_cmp
	s_mul_i32 s1, s32, 0x180
	s_add_i32 s0, s0, s1
	s_cmpk_lt_u32 s0, 0x480
	s_cselect_b32 s26, s0, 0x480
	s_branch .Lp2_have
.Lp2_cmp:
	s_cmp_eq_u32 s32, 0
	s_cselect_b32 s26, s0, 0x480
.Lp2_have:
	s_add_i32 s32, s32, 1
	s_mov_b64 s[0:1], -1
	s_cmpk_gt_u32 s26, 0x47f
	s_cbranch_scc1 .LBB0_341
	s_waitcnt vmcnt(0)
	v_mov_b32_e32 v80, v200
	s_cmpk_gt_i32 s26, 0x7f
	s_cbranch_scc0 .LBB0_395
	s_add_i32 s1, s26, 0xffffff80
	s_bfe_u32 s16, s26, 0x30002
	s_lshr_b32 s17, s1, 5
	s_and_b32 s0, s26, 3
	s_lshl_b32 s2, s17, 6
	s_lshl_b32 s4, s16, 11
	s_add_i32 s2, s2, s4
	s_lshl_b32 s4, s16, 7
	s_lshl_b32 s5, s0, 5
	s_or_b32 s6, s4, s5
	s_add_i32 s4, s6, s17
	s_mulk_i32 s4, 0x140
	s_mov_b32 s5, s3
	s_lshl_b64 s[4:5], s[4:5], 2
	s_add_u32 s12, s70, s4
	s_waitcnt vmcnt(0)
	v_and_b32_e32 v104, 63, v80
	s_addc_u32 s13, s71, s5
	v_cmp_gt_u32_e32 vcc, 64, v80
	s_and_saveexec_b64 s[14:15], vcc
	s_cbranch_execz .LBB0_356
	v_cmp_gt_u32_e32 vcc, s17, v104
	v_mov_b32_e32 v2, 0
	v_mov_b32_e32 v0, 0
	v_mov_b32_e32 v1, 0
	s_and_saveexec_b64 s[4:5], vcc
	s_cbranch_execz .LBB0_351
	s_lshl_b32 s6, s6, 3
	s_add_u32 s6, s88, s6
	s_addc_u32 s7, s89, 0
	v_lshlrev_b32_e32 v196, 1, v80
	v_lshl_add_u64 v[0:1], v[196:197], 2, s[6:7]
	global_load_dwordx2 v[0:1], v[0:1], off
